# clique barrier poll loop without s_sleep (4 clique sites), nt hints as before
# baseline (speedup 1.0000x reference)
.Lxq_spin_0:
	global_load_dword v2, v[0:1], off sc1
	s_add_u32 s7, s7, 1
	s_waitcnt vmcnt(0)
	v_sub_u32_e32 v2, v2, v3
	v_cmp_le_i32_e32 vcc, 0, v2
	s_cbranch_vccnz .Lxq_done_0
	s_cmp_gt_u32 s7, 0x8000
	s_cbranch_scc1 .Lxq_done_0
	s_branch .Lxq_spin_0
